# HG_H3 second MFMA block: eight fragment reads issued together, counted lgkmcnt waits
# speedup vs baseline: 1.0007x; 1.0007x over previous
; #define LAS __attribute__((address_space(3)))
; __device__ __forceinline__ unsigned pk2(float lo, float hi) { f32x2c v = {lo, hi}; return __builtin_bit_cast(unsigned, __builtin_convertvector(v, bf16x2c)); }
; __device__ __forceinline__ void hgrn_h3(LAS unsigned char* lds8, const int e) {
;     ...
;         const int fr = lane & 15, fq = lane >> 4;
;         f32x4 acc[4];
; #pragma unroll
;         for (int I = 0; I < 4; ++I) acc[I] = (f32x4){0.f, 0.f, 0.f, 0.f};
; #pragma unroll
;         for (int ks = 0; ks < 4; ++ks) { const bf16x8 a = *(const LAS bf16x8*)(ST + (16 * wave + fr) * RS128 + 32 * ks + 8 * fq);
; #pragma unroll
;             for (int I = 0; I < 4; ++I) { const bf16x8 bb = *(const LAS bf16x8*)(Qb + (16 * I + fr) * RS128 + 32 * ks + 8 * fq);
;                 acc[I] = __builtin_amdgcn_mfma_f32_16x16x32_bf16(a, bb, acc[I], 0, 0, 0); } }
; #pragma unroll
;         for (int I = 0; I < 4; ++I) {
;             const int rb = 8 * I * (I + 1);
;             f32x4 P[4];
; #pragma unroll
;             for (int Jt = 0; Jt < 4; ++Jt) { P[Jt] = (f32x4){0.f, 0.f, 0.f, 0.f};
;                 if (Jt <= I) {
; #pragma unroll
;                     for (int ks = 0; ks < 4; ++ks) { const bf16x8 a = *(const LAS bf16x8*)(KT + (rb + 16 * Jt + fr) * RS128 + 32 * ks + 8 * fq);
;                         const bf16x8 bb = *(const LAS bf16x8*)(Qt + (16 * I + fr) * RS128 + 32 * ks + 8 * fq);
;                         P[Jt] = __builtin_amdgcn_mfma_f32_16x16x32_bf16(a, bb, P[Jt], 0, 0, 0); }
;                     if (Jt == I) {
; #pragma unroll
;                         for (int r = 0; r < 4; ++r) P[Jt][r] = (4 * fq + r <= fr) ? P[Jt][r] : 0.f; }
;                 } }
; #pragma unroll
;             for (int s = 0; s < 2; ++s) if (2 * s <= I) {
;                 u32x4 pw; pw.x = pk2(P[2 * s][0], P[2 * s][1]); pw.y = pk2(P[2 * s][2], P[2 * s][3]); pw.z = pk2(P[2 * s + 1][0], P[2 * s + 1][1]); pw.w = pk2(P[2 * s + 1][2], P[2 * s + 1][3]);
;                 const s16x4 v0 = *(const LAS s16x4*)(VT + (16 * wave + fr) * RS64 + 32 * s + 4 * fq), v1 = *(const LAS s16x4*)(VT + (16 * wave + fr) * RS64 + 32 * s + 16 + 4 * fq);
;                 const bf16x8 a = (bf16x8){v0[0], v0[1], v0[2], v0[3], v1[0], v1[1], v1[2], v1[3]};
;                 acc[I] = __builtin_amdgcn_mfma_f32_16x16x32_bf16(a, __builtin_bit_cast(bf16x8, pw), acc[I], 0, 0, 0); }
.LBB0_754:
	s_or_b64 exec, exec, s[30:31]
	s_waitcnt lgkmcnt(0)
	s_barrier
	ds_read_b128 v[4:7], v53
	ds_read_b128 v[8:11], v79 offset:17408
	ds_read_b128 v[12:15], v79 offset:21760
	ds_read_b128 v[16:19], v79 offset:26112
	ds_read_b128 v[20:23], v79 offset:30464
	ds_read_b128 v[192:195], v53 offset:64
	ds_read_b128 v[196:199], v79 offset:17472
	ds_read_b128 v[200:203], v79 offset:21824
	ds_read_b128 v[204:207], v79 offset:26176
	ds_read_b128 v[208:211], v79 offset:30528
	ds_read_b128 v[212:215], v53 offset:128
	ds_read_b128 v[216:219], v79 offset:17536
	ds_read_b128 v[220:223], v79 offset:21888
	ds_read_b128 v[224:227], v79 offset:26240
	ds_read_b128 v[228:231], v79 offset:30592
	s_waitcnt lgkmcnt(13)
	v_mfma_f32_16x16x32_bf16 v[8:11], v[4:7], v[8:11], 0
	s_add_i32 s66, s66, s46
	s_add_i32 s4, s4, s5
	s_add_i32 s28, s28, s34
	s_waitcnt lgkmcnt(12)
	v_mfma_f32_16x16x32_bf16 v[12:15], v[4:7], v[12:15], 0
	v_lshl_add_u64 v[32:33], v[32:33], 0, s[2:3]
	s_cmpk_lt_i32 s66, 0x400
	s_waitcnt lgkmcnt(11)
	v_mfma_f32_16x16x32_bf16 v[16:19], v[4:7], v[16:19], 0
	s_waitcnt lgkmcnt(10)
	v_mfma_f32_16x16x32_bf16 v[4:7], v[4:7], v[20:23], 0
	ds_read_b128 v[236:239], v53 offset:192
	ds_read_b128 v[240:243], v79 offset:17600
	ds_read_b128 v[244:247], v79 offset:21952
	s_waitcnt lgkmcnt(11)
	v_mfma_f32_16x16x32_bf16 v[8:11], v[192:195], v[196:199], v[8:11]
	s_waitcnt lgkmcnt(10)
	v_mfma_f32_16x16x32_bf16 v[12:15], v[192:195], v[200:203], v[12:15]
	s_waitcnt lgkmcnt(9)
	v_mfma_f32_16x16x32_bf16 v[16:19], v[192:195], v[204:207], v[16:19]
	s_waitcnt lgkmcnt(8)
	v_mfma_f32_16x16x32_bf16 v[4:7], v[192:195], v[208:211], v[4:7]
	s_waitcnt lgkmcnt(6)
	v_mfma_f32_16x16x32_bf16 v[8:11], v[212:215], v[216:219], v[8:11]
	s_waitcnt lgkmcnt(5)
	v_mfma_f32_16x16x32_bf16 v[12:15], v[212:215], v[220:223], v[12:15]
	s_waitcnt lgkmcnt(4)
	v_mfma_f32_16x16x32_bf16 v[16:19], v[212:215], v[224:227], v[16:19]
	s_waitcnt lgkmcnt(3)
	v_mfma_f32_16x16x32_bf16 v[4:7], v[212:215], v[228:231], v[4:7]
	s_waitcnt lgkmcnt(1)
	v_mfma_f32_16x16x32_bf16 v[8:11], v[236:239], v[240:243], v[8:11]
	s_waitcnt lgkmcnt(0)
	v_mfma_f32_16x16x32_bf16 v[82:85], v[236:239], v[244:247], v[12:15]
	s_nop 2
	ds_read_b128 v[12:15], v79 offset:26304
	s_waitcnt lgkmcnt(0)
	v_mfma_f32_16x16x32_bf16 v[20:23], v[236:239], v[12:15], v[16:19]
	ds_read_b128 v[12:15], v79 offset:30656
	s_waitcnt lgkmcnt(0)
	v_mfma_f32_16x16x32_bf16 v[4:7], v[236:239], v[12:15], v[4:7]
	ds_read_b128 v[12:15], v79 offset:34816
	ds_read_b128 v[16:19], v79
	ds_read_b128 v[192:195], v79 offset:34880
	ds_read_b128 v[24:27], v79 offset:64
	ds_read_b128 v[196:199], v79 offset:34944
	ds_read_b128 v[200:203], v79 offset:128
	ds_read_b128 v[204:207], v79 offset:35008
	ds_read_b128 v[208:211], v79 offset:192
	s_waitcnt lgkmcnt(6)
	v_mfma_f32_16x16x32_bf16 v[12:15], v[12:15], v[16:19], 0
	s_waitcnt lgkmcnt(4)
	v_mfma_f32_16x16x32_bf16 v[12:15], v[192:195], v[24:27], v[12:15]
	s_waitcnt lgkmcnt(2)
	v_mfma_f32_16x16x32_bf16 v[12:15], v[196:199], v[200:203], v[12:15]
	s_waitcnt lgkmcnt(0)
	v_mfma_f32_16x16x32_bf16 v[12:15], v[204:207], v[208:211], v[12:15]
	v_mov_b32_e32 v18, v3
	v_mov_b32_e32 v19, v3
	s_nop 5
	v_cndmask_b32_e64 v12, v12, 0, s[20:21]
	v_cndmask_b32_e64 v13, 0, v13, s[22:23]
	v_cndmask_b32_e64 v14, v14, 0, s[24:25]
	v_cndmask_b32_e64 v15, v15, 0, s[26:27]
	v_cvt_pk_bf16_f32 v16, v12, v13
	v_cvt_pk_bf16_f32 v17, v14, v15
	ds_read2_b64 v[12:15], v81 offset1:4
	s_waitcnt lgkmcnt(0)
	v_mfma_f32_16x16x32_bf16 v[8:11], v[12:15], v[16:19], v[8:11]
	ds_read_b128 v[16:19], v79 offset:39168
	ds_read_b128 v[24:27], v79 offset:4352
	ds_read_b128 v[86:89], v79 offset:39232
	ds_read_b128 v[90:93], v79 offset:4416
	ds_read_b128 v[192:195], v79 offset:39296
	ds_read_b128 v[94:97], v79 offset:4480
	ds_read_b128 v[196:199], v79 offset:39360
	ds_read_b128 v[98:101], v79 offset:4544
	ds_read_b128 v[200:203], v79 offset:43520
	ds_read_b128 v[204:207], v79 offset:43584
	ds_read_b128 v[208:211], v79 offset:43648
	ds_read_b128 v[212:215], v79 offset:43712
	s_waitcnt lgkmcnt(10)
	v_mfma_f32_16x16x32_bf16 v[16:19], v[16:19], v[24:27], 0
	s_waitcnt lgkmcnt(8)
	v_mfma_f32_16x16x32_bf16 v[16:19], v[86:89], v[90:93], v[16:19]
	s_waitcnt lgkmcnt(6)
	v_mfma_f32_16x16x32_bf16 v[16:19], v[192:195], v[94:97], v[16:19]
	s_waitcnt lgkmcnt(4)
	v_mfma_f32_16x16x32_bf16 v[16:19], v[196:199], v[98:101], v[16:19]
	s_waitcnt lgkmcnt(3)
	v_mfma_f32_16x16x32_bf16 v[24:27], v[200:203], v[24:27], 0
	s_nop 4
	v_cvt_pk_bf16_f32 v16, v16, v17
	v_cvt_pk_bf16_f32 v17, v18, v19
	s_waitcnt lgkmcnt(2)
	v_mfma_f32_16x16x32_bf16 v[24:27], v[204:207], v[90:93], v[24:27]
	s_waitcnt lgkmcnt(1)
	v_mfma_f32_16x16x32_bf16 v[24:27], v[208:211], v[94:97], v[24:27]
	s_waitcnt lgkmcnt(0)
	v_mfma_f32_16x16x32_bf16 v[24:27], v[212:215], v[98:101], v[24:27]
	s_nop 7
	v_cndmask_b32_e64 v24, v24, 0, s[20:21]
	v_cndmask_b32_e64 v25, 0, v25, s[22:23]
	v_cndmask_b32_e64 v26, v26, 0, s[24:25]
	v_cndmask_b32_e64 v27, v27, 0, s[26:27]
	v_cvt_pk_bf16_f32 v18, v24, v25
	v_cvt_pk_bf16_f32 v19, v26, v27
	s_nop 1
	v_mfma_f32_16x16x32_bf16 v[16:19], v[12:15], v[16:19], v[82:85]
	ds_read_b128 v[24:27], v79 offset:47872
	s_nop 1
	ds_read_b128 v[82:85], v79 offset:8704
	ds_read_b128 v[86:89], v79 offset:47936
	ds_read_b128 v[90:93], v79 offset:8768
	s_waitcnt lgkmcnt(2)
	v_mfma_f32_16x16x32_bf16 v[24:27], v[24:27], v[82:85], 0
	s_waitcnt lgkmcnt(0)
	v_mfma_f32_16x16x32_bf16 v[24:27], v[86:89], v[90:93], v[24:27]
	ds_read_b128 v[86:89], v79 offset:48000
	ds_read_b128 v[94:97], v79 offset:8832
	s_waitcnt lgkmcnt(0)
; #define LAS __attribute__((address_space(3)))
; __device__ __forceinline__ unsigned pk2(float lo, float hi) { f32x2c v = {lo, hi}; return __builtin_bit_cast(unsigned, __builtin_convertvector(v, bf16x2c)); }
; __device__ __forceinline__ void hgrn_h3(LAS unsigned char* lds8, const int e) {
;     ...
;         for (int I = 0; I < 4; ++I) {
;             const int rb = 8 * I * (I + 1);
;             f32x4 P[4];
; #pragma unroll
;             for (int Jt = 0; Jt < 4; ++Jt) { P[Jt] = (f32x4){0.f, 0.f, 0.f, 0.f};
;                 if (Jt <= I) {
; #pragma unroll
;                     for (int ks = 0; ks < 4; ++ks) { const bf16x8 a = *(const LAS bf16x8*)(KT + (rb + 16 * Jt + fr) * RS128 + 32 * ks + 8 * fq);
;                         const bf16x8 bb = *(const LAS bf16x8*)(Qt + (16 * I + fr) * RS128 + 32 * ks + 8 * fq);
;                         P[Jt] = __builtin_amdgcn_mfma_f32_16x16x32_bf16(a, bb, P[Jt], 0, 0, 0); }
;                     if (Jt == I) {
; #pragma unroll
;                         for (int r = 0; r < 4; ++r) P[Jt][r] = (4 * fq + r <= fr) ? P[Jt][r] : 0.f; }
;                 } }
; #pragma unroll
;             for (int s = 0; s < 2; ++s) if (2 * s <= I) {
;                 u32x4 pw; pw.x = pk2(P[2 * s][0], P[2 * s][1]); pw.y = pk2(P[2 * s][2], P[2 * s][3]); pw.z = pk2(P[2 * s + 1][0], P[2 * s + 1][1]); pw.w = pk2(P[2 * s + 1][2], P[2 * s + 1][3]);
;                 const s16x4 v0 = *(const LAS s16x4*)(VT + (16 * wave + fr) * RS64 + 32 * s + 4 * fq), v1 = *(const LAS s16x4*)(VT + (16 * wave + fr) * RS64 + 32 * s + 16 + 4 * fq);
;                 const bf16x8 a = (bf16x8){v0[0], v0[1], v0[2], v0[3], v1[0], v1[1], v1[2], v1[3]};
;                 acc[I] = __builtin_amdgcn_mfma_f32_16x16x32_bf16(a, __builtin_bit_cast(bf16x8, pw), acc[I], 0, 0, 0); }
;         }
; #pragma unroll
;         for (int I = 0; I < 4; ++I) *(f32x4*)(O0 + (size_t)(m0 + 16 * I + fr) * 1024 + h * 128 + 16 * wave + 4 * fq) = acc[I];
	v_mfma_f32_16x16x32_bf16 v[24:27], v[86:89], v[94:97], v[24:27]
	ds_read_b128 v[86:89], v79 offset:48064
	ds_read_b128 v[98:101], v79 offset:8896
	ds_read_b128 v[102:105], v79 offset:52288
	s_waitcnt lgkmcnt(1)
	v_mfma_f32_16x16x32_bf16 v[24:27], v[86:89], v[98:101], v[24:27]
	ds_read_b128 v[86:89], v79 offset:52224
	s_waitcnt lgkmcnt(0)
	v_mfma_f32_16x16x32_bf16 v[86:89], v[86:89], v[82:85], 0
	s_nop 4
	v_cvt_pk_bf16_f32 v24, v24, v25
	v_cvt_pk_bf16_f32 v25, v26, v27
	v_mfma_f32_16x16x32_bf16 v[86:89], v[102:105], v[90:93], v[86:89]
	ds_read_b128 v[102:105], v79 offset:52352
	s_waitcnt lgkmcnt(0)
	v_mfma_f32_16x16x32_bf16 v[86:89], v[102:105], v[94:97], v[86:89]
	ds_read_b128 v[102:105], v79 offset:52416
	s_waitcnt lgkmcnt(0)
	v_mfma_f32_16x16x32_bf16 v[86:89], v[102:105], v[98:101], v[86:89]
	ds_read_b128 v[102:105], v79 offset:56576
	s_nop 6
	v_cvt_pk_bf16_f32 v26, v86, v87
	s_waitcnt lgkmcnt(0)
	v_mfma_f32_16x16x32_bf16 v[82:85], v[102:105], v[82:85], 0
	ds_read_b128 v[102:105], v79 offset:56640
	v_cvt_pk_bf16_f32 v27, v88, v89
	s_waitcnt lgkmcnt(0)
	v_mfma_f32_16x16x32_bf16 v[82:85], v[102:105], v[90:93], v[82:85]
	ds_read_b128 v[90:93], v79 offset:56704
	s_waitcnt lgkmcnt(0)
	v_mfma_f32_16x16x32_bf16 v[82:85], v[90:93], v[94:97], v[82:85]
	ds_read_b128 v[90:93], v79 offset:56768
	v_mfma_f32_16x16x32_bf16 v[20:23], v[12:15], v[24:27], v[20:23]
	ds_read2_b64 v[24:27], v81 offset0:8 offset1:12
	s_waitcnt lgkmcnt(1)
	v_mfma_f32_16x16x32_bf16 v[82:85], v[90:93], v[98:101], v[82:85]
	s_nop 7
	v_cndmask_b32_e64 v82, v82, 0, s[20:21]
	v_cndmask_b32_e64 v83, 0, v83, s[22:23]
	v_cndmask_b32_e64 v84, v84, 0, s[24:25]
	v_cndmask_b32_e64 v85, v85, 0, s[26:27]
	v_cvt_pk_bf16_f32 v82, v82, v83
	v_cvt_pk_bf16_f32 v83, v84, v85
	v_mov_b32_e32 v84, v3
	v_mov_b32_e32 v85, v3
	s_waitcnt lgkmcnt(0)
	s_nop 0
	v_mfma_f32_16x16x32_bf16 v[20:23], v[24:27], v[82:85], v[20:23]
	ds_read_b128 v[82:85], v79 offset:60928
	ds_read_b128 v[86:89], v79 offset:13056
	ds_read_b128 v[90:93], v79 offset:60992
	ds_read_b128 v[94:97], v79 offset:13120
	s_waitcnt lgkmcnt(2)
	v_mfma_f32_16x16x32_bf16 v[82:85], v[82:85], v[86:89], 0
	s_waitcnt lgkmcnt(0)
	v_mfma_f32_16x16x32_bf16 v[82:85], v[90:93], v[94:97], v[82:85]
	ds_read_b128 v[90:93], v79 offset:61056
	ds_read_b128 v[98:101], v79 offset:13184
	s_waitcnt lgkmcnt(0)
	v_mfma_f32_16x16x32_bf16 v[82:85], v[90:93], v[98:101], v[82:85]
	ds_read_b128 v[90:93], v79 offset:61120
	ds_read_b128 v[102:105], v79 offset:13248
	ds_read_b128 v[106:109], v79 offset:65344
	ds_read_b128 v[110:113], v80 offset:34880
	s_waitcnt lgkmcnt(2)
	v_mfma_f32_16x16x32_bf16 v[82:85], v[90:93], v[102:105], v[82:85]
	ds_read_b128 v[90:93], v79 offset:65280
	s_waitcnt lgkmcnt(0)
	v_mfma_f32_16x16x32_bf16 v[90:93], v[90:93], v[86:89], 0
	s_nop 4
	v_cvt_pk_bf16_f32 v82, v82, v83
	v_cvt_pk_bf16_f32 v83, v84, v85
	v_mfma_f32_16x16x32_bf16 v[90:93], v[106:109], v[94:97], v[90:93]
	ds_read_b128 v[106:109], v79 offset:65408
	s_waitcnt lgkmcnt(0)
	v_mfma_f32_16x16x32_bf16 v[90:93], v[106:109], v[98:101], v[90:93]
	ds_read_b128 v[106:109], v79 offset:65472
	s_waitcnt lgkmcnt(0)
	v_mfma_f32_16x16x32_bf16 v[90:93], v[106:109], v[102:105], v[90:93]
	ds_read_b128 v[106:109], v80 offset:34816
	s_nop 6
	v_cvt_pk_bf16_f32 v84, v90, v91
	s_waitcnt lgkmcnt(0)
	v_mfma_f32_16x16x32_bf16 v[106:109], v[106:109], v[86:89], 0
	v_cvt_pk_bf16_f32 v85, v92, v93
	v_mfma_f32_16x16x32_bf16 v[106:109], v[110:113], v[94:97], v[106:109]
	ds_read_b128 v[110:113], v80 offset:34944
	s_waitcnt lgkmcnt(0)
	v_mfma_f32_16x16x32_bf16 v[106:109], v[110:113], v[98:101], v[106:109]
	ds_read_b128 v[110:113], v80 offset:35008
	s_waitcnt lgkmcnt(0)
	v_mfma_f32_16x16x32_bf16 v[106:109], v[110:113], v[102:105], v[106:109]
	ds_read_b128 v[110:113], v80 offset:39168
	s_waitcnt lgkmcnt(0)
	v_mfma_f32_16x16x32_bf16 v[86:89], v[110:113], v[86:89], 0
	ds_read_b128 v[110:113], v80 offset:39232
	s_waitcnt lgkmcnt(0)
	v_mfma_f32_16x16x32_bf16 v[86:89], v[110:113], v[94:97], v[86:89]
	ds_read_b128 v[94:97], v80 offset:39296
	s_waitcnt lgkmcnt(0)
	v_mfma_f32_16x16x32_bf16 v[86:89], v[94:97], v[98:101], v[86:89]
	ds_read_b128 v[94:97], v80 offset:39360
	s_waitcnt lgkmcnt(0)
	v_mfma_f32_16x16x32_bf16 v[86:89], v[94:97], v[102:105], v[86:89]
	s_nop 7
	v_cndmask_b32_e64 v86, v86, 0, s[20:21]
	v_mfma_f32_16x16x32_bf16 v[4:7], v[12:15], v[82:85], v[4:7]
	v_cndmask_b32_e64 v87, 0, v87, s[22:23]
	v_cndmask_b32_e64 v88, v88, 0, s[24:25]
	v_cndmask_b32_e64 v89, v89, 0, s[26:27]
	v_cvt_pk_bf16_f32 v12, v106, v107
	v_cvt_pk_bf16_f32 v13, v108, v109
	v_cvt_pk_bf16_f32 v14, v86, v87
	v_cvt_pk_bf16_f32 v15, v88, v89
	s_nop 1
	v_mfma_f32_16x16x32_bf16 v[4:7], v[24:27], v[12:15], v[4:7]
	v_or_b32_e32 v12, s35, v52
	v_ashrrev_i32_e32 v13, 31, v12
	v_lshl_add_u64 v[14:15], s[52:53], 2, v[28:29]
	v_lshlrev_b64 v[24:25], 12, v[12:13]
	v_lshl_add_u64 v[24:25], v[14:15], 0, v[24:25]
	global_store_dwordx4 v[24:25], v[8:11], off
	s_nop 1
	v_or_b32_e32 v8, 16, v12
	v_ashrrev_i32_e32 v9, 31, v8
	v_lshlrev_b64 v[8:9], 12, v[8:9]
	v_lshl_add_u64 v[8:9], v[14:15], 0, v[8:9]
	global_store_dwordx4 v[8:9], v[16:19], off
	v_or_b32_e32 v8, 32, v12
	v_ashrrev_i32_e32 v9, 31, v8
	v_lshlrev_b64 v[8:9], 12, v[8:9]
	v_lshl_add_u64 v[8:9], v[14:15], 0, v[8:9]
	global_store_dwordx4 v[8:9], v[20:23], off
	v_or_b32_e32 v8, 48, v12
	v_ashrrev_i32_e32 v9, 31, v8
	v_lshlrev_b64 v[8:9], 12, v[8:9]
	v_lshl_add_u64 v[8:9], v[14:15], 0, v[8:9]
	global_store_dwordx4 v[8:9], v[4:7], off
	s_cbranch_scc0 .LBB0_887
